# code placement: 64-byte alignment of the ten hot loop headers (six GEMM K-loops, selected stage loop, compressed-pass loops, window loop); no instruction changed
# baseline (speedup 1.0000x reference)
; template <class Epi, class Sched, bool ALIGN_EPI = false, bool SP2 = false>
; __device__ __forceinline__ void gemm_phase(PG8_LAS unsigned char* lds, const int Kdim, const Sched& S, const Epi& E) {
;     ...
; #pragma unroll
;         for (int a = 0; a < 2; ++a)
; #pragma unroll
;             for (int b = 0; b < 2; ++b)
; #pragma unroll
;                 for (int m = 0; m < 4; ++m)
; #pragma unroll
;                     for (int n = 0; n < 2; ++n) acc[a][b][m][n] = (f32x4){0.f, 0.f, 0.f, 0.f};
;         cur = nxt; cA = nA; cB = nB; ++ui;
.LBB0_213:
	s_add_u32 s2, s62, 0x40080
	s_addc_u32 s3, s63, 0
	s_add_u32 s8, s60, 0x100
	v_mov_b32_e32 v2, 0
	s_addc_u32 s64, s61, 0
	s_mov_b32 s65, -2
	v_mov_b32_e32 v3, v2
	v_mov_b32_e32 v4, v2
	v_mov_b32_e32 v5, v2
	v_mov_b32_e32 v6, v2
	v_mov_b32_e32 v7, v2
	v_mov_b32_e32 v8, v2
	v_mov_b32_e32 v9, v2
	v_mov_b32_e32 v18, v2
	v_mov_b32_e32 v19, v2
	v_mov_b32_e32 v20, v2
	v_mov_b32_e32 v21, v2
	v_mov_b32_e32 v22, v2
	v_mov_b32_e32 v23, v2
	v_mov_b32_e32 v24, v2
	v_mov_b32_e32 v25, v2
	v_mov_b32_e32 v34, v2
	v_mov_b32_e32 v35, v2
	v_mov_b32_e32 v36, v2
	v_mov_b32_e32 v37, v2
	v_mov_b32_e32 v38, v2
	v_mov_b32_e32 v39, v2
	v_mov_b32_e32 v40, v2
	v_mov_b32_e32 v41, v2
	v_mov_b32_e32 v50, v2
	v_mov_b32_e32 v51, v2
	v_mov_b32_e32 v52, v2
	v_mov_b32_e32 v53, v2
	v_mov_b32_e32 v54, v2
	v_mov_b32_e32 v55, v2
	v_mov_b32_e32 v56, v2
	v_mov_b32_e32 v57, v2
	v_mov_b32_e32 v10, v2
	v_mov_b32_e32 v11, v2
	v_mov_b32_e32 v12, v2
	v_mov_b32_e32 v13, v2
	v_mov_b32_e32 v14, v2
	v_mov_b32_e32 v15, v2
	v_mov_b32_e32 v16, v2
	v_mov_b32_e32 v17, v2
	v_mov_b32_e32 v26, v2
	v_mov_b32_e32 v27, v2
	v_mov_b32_e32 v28, v2
	v_mov_b32_e32 v29, v2
	v_mov_b32_e32 v30, v2
	v_mov_b32_e32 v31, v2
	v_mov_b32_e32 v32, v2
	v_mov_b32_e32 v33, v2
	v_mov_b32_e32 v42, v2
	v_mov_b32_e32 v43, v2
	v_mov_b32_e32 v44, v2
	v_mov_b32_e32 v45, v2
	v_mov_b32_e32 v46, v2
	v_mov_b32_e32 v47, v2
	v_mov_b32_e32 v48, v2
	v_mov_b32_e32 v49, v2
	v_mov_b32_e32 v58, v2
	v_mov_b32_e32 v59, v2
	v_mov_b32_e32 v60, v2
	v_mov_b32_e32 v61, v2
	v_mov_b32_e32 v62, v2
	v_mov_b32_e32 v63, v2
	v_mov_b32_e32 v64, v2
	v_mov_b32_e32 v65, v2
	v_mov_b32_e32 v66, v2
	v_mov_b32_e32 v67, v2
	v_mov_b32_e32 v68, v2
	v_mov_b32_e32 v69, v2
	v_mov_b32_e32 v70, v2
	v_mov_b32_e32 v71, v2
	v_mov_b32_e32 v72, v2
	v_mov_b32_e32 v73, v2
	v_mov_b32_e32 v82, v2
	v_mov_b32_e32 v83, v2
	v_mov_b32_e32 v84, v2
	v_mov_b32_e32 v85, v2
	v_mov_b32_e32 v86, v2
	v_mov_b32_e32 v87, v2
	v_mov_b32_e32 v88, v2
	v_mov_b32_e32 v89, v2
	v_mov_b32_e32 v98, v2
	v_mov_b32_e32 v99, v2
	v_mov_b32_e32 v100, v2
	v_mov_b32_e32 v101, v2
	v_mov_b32_e32 v102, v2
	v_mov_b32_e32 v103, v2
	v_mov_b32_e32 v104, v2
	v_mov_b32_e32 v105, v2
	v_mov_b32_e32 v114, v2
	v_mov_b32_e32 v115, v2
	v_mov_b32_e32 v116, v2
	v_mov_b32_e32 v117, v2
	v_mov_b32_e32 v118, v2
	v_mov_b32_e32 v119, v2
	v_mov_b32_e32 v120, v2
	v_mov_b32_e32 v121, v2
	v_mov_b32_e32 v74, v2
	v_mov_b32_e32 v75, v2
	v_mov_b32_e32 v76, v2
	v_mov_b32_e32 v77, v2
	v_mov_b32_e32 v78, v2
	v_mov_b32_e32 v79, v2
	v_mov_b32_e32 v80, v2
	v_mov_b32_e32 v81, v2
	v_mov_b32_e32 v90, v2
	v_mov_b32_e32 v91, v2
	v_mov_b32_e32 v92, v2
	v_mov_b32_e32 v93, v2
	v_mov_b32_e32 v94, v2
	v_mov_b32_e32 v95, v2
	v_mov_b32_e32 v96, v2
	v_mov_b32_e32 v97, v2
	v_mov_b32_e32 v106, v2
	v_mov_b32_e32 v107, v2
	v_mov_b32_e32 v108, v2
	v_mov_b32_e32 v109, v2
	v_mov_b32_e32 v110, v2
	v_mov_b32_e32 v111, v2
	v_mov_b32_e32 v112, v2
	v_mov_b32_e32 v113, v2
	v_mov_b32_e32 v122, v2
	v_mov_b32_e32 v123, v2
	v_mov_b32_e32 v124, v2
	v_mov_b32_e32 v125, v2
	v_mov_b32_e32 v126, v2
	v_mov_b32_e32 v127, v2
	v_mov_b32_e32 v128, v2
	v_mov_b32_e32 v129, v2
	.p2align	6

; DEV unsigned cvtpk(float lo, float hi) { typedef float f2 __attribute__((ext_vector_type(2))); typedef __bf16 b2 __attribute__((ext_vector_type(2))); f2 v = {lo, hi}; b2 b = __builtin_convertvector(v, b2); return __builtin_bit_cast(unsigned, b); }
; DEV void ref_step(f32x4 (&s)[4], float& m, f32x4 (&O)[4], f32x4& L, ab8 (&pf)[2], bool colact) {
;     ...
; #pragma unroll
;     for (int kt = 0; kt < 4; ++kt)
; #pragma unroll
;         for (int i = 0; i < 4; ++i) s[kt][i] = __builtin_amdgcn_exp2f(s[kt][i]);
; #pragma unroll
;     for (int j = 0; j < 2; ++j) { v4u w; w.x = cvtpk(s[2 * j][0], s[2 * j][1]); w.y = cvtpk(s[2 * j][2], s[2 * j][3]); w.z = cvtpk(s[2 * j + 1][0], s[2 * j + 1][1]); w.w = cvtpk(s[2 * j + 1][2], s[2 * j + 1][3]); pf[j] = __builtin_bit_cast(ab8, w); }
; template <bool PV, bool WITHL>
; DEV void pv64(const LAS unsigned char* Vb, const AttnCtx& C, const ab8 (&pf)[2][2], f32x4 (&O)[2][4], f32x4 (&L)[2], bool a0, bool a1) {
;     ...
;     if (WITHL) {
;         const short one = (C.n == 0) ? (short)0x3F80 : (short)0; const ab8 ones = {one, one, one, one, one, one, one, one};
; #pragma unroll
;         for (int j = 0; j < 2; ++j) {
;             if (a0) L[0] = __builtin_amdgcn_mfma_f32_16x16x32_bf16(ones, pf[0][j], L[0], 0, 0, 0);
;             if (a1) L[1] = __builtin_amdgcn_mfma_f32_16x16x32_bf16(ones, pf[1][j], L[1], 0, 0, 0);
;         }
.LBB0_920:
	v_exp_f32_e32 v18, v94
	v_exp_f32_e32 v21, v95
	v_exp_f32_e32 v94, v96
	v_exp_f32_e32 v96, v90
	v_exp_f32_e32 v95, v97
	v_cvt_pk_bf16_f32 v90, v18, v21
	v_exp_f32_e32 v18, v82
	v_exp_f32_e32 v21, v83
	v_exp_f32_e32 v83, v84
	v_exp_f32_e32 v84, v85
	v_exp_f32_e32 v85, v86
	v_exp_f32_e32 v86, v87
	v_exp_f32_e32 v87, v88
	v_exp_f32_e32 v88, v89
	v_cvt_pk_bf16_f32 v82, v18, v21
	v_exp_f32_e32 v18, v70
	v_exp_f32_e32 v21, v71
	v_exp_f32_e32 v71, v72
	v_exp_f32_e32 v72, v73
	v_exp_f32_e32 v73, v74
	v_exp_f32_e32 v74, v75
	v_exp_f32_e32 v75, v76
	v_exp_f32_e32 v76, v77
	v_exp_f32_e32 v97, v91
	v_exp_f32_e32 v113, v92
	v_exp_f32_e32 v93, v93
	v_cvt_pk_bf16_f32 v83, v83, v84
	v_cvt_pk_bf16_f32 v84, v85, v86
	v_cvt_pk_bf16_f32 v85, v87, v88
	v_exp_f32_e32 v77, v78
	v_exp_f32_e32 v78, v79
	v_exp_f32_e32 v79, v80
	v_exp_f32_e32 v80, v81
	v_exp_f32_e32 v81, v66
	v_exp_f32_e32 v86, v67
	v_cvt_pk_bf16_f32 v70, v18, v21
	v_cvt_pk_bf16_f32 v71, v71, v72
	v_cvt_pk_bf16_f32 v72, v73, v74
	v_cvt_pk_bf16_f32 v73, v75, v76
	v_exp_f32_e32 v18, v68
	v_exp_f32_e32 v21, v69
	v_mfma_f32_16x16x32_bf16 v[62:65], v[22:25], v[82:85], v[62:65]
	v_cvt_pk_bf16_f32 v91, v94, v95
	v_cvt_pk_bf16_f32 v92, v96, v97
	v_cvt_pk_bf16_f32 v93, v113, v93
	v_mfma_f32_16x16x32_bf16 v[58:61], v[22:25], v[70:73], v[58:61]
	v_cvt_pk_bf16_f32 v66, v77, v78
	v_cvt_pk_bf16_f32 v67, v79, v80
	v_cvt_pk_bf16_f32 v68, v81, v86
	v_cvt_pk_bf16_f32 v69, v18, v21
	v_mfma_f32_16x16x32_bf16 v[62:65], v[22:25], v[90:93], v[62:65]
	s_addk_i32 s23, 0x400
	s_addk_i32 s25, 0x4000
	s_add_i32 s24, s24, 1
	v_mfma_f32_16x16x32_bf16 v[58:61], v[22:25], v[66:69], v[58:61]
	s_add_i32 s86, s86, 64
	s_add_i32 s10, s26, -1
	v_add_u32_e32 v112, 0xfffffc00, v112
	v_add_u32_e32 v110, 0x4000, v110
	s_cmp_eq_u32 s10, s16
	v_add_u32_e32 v111, 0x4000, v111
	s_cbranch_scc1 .LBB0_939
	.p2align	6

; DEV s16x4 vtr(const LAS unsigned char* p) { typedef short v4i16_t __attribute__((ext_vector_type(4))); return __builtin_bit_cast(s16x4, __builtin_amdgcn_ds_read_tr16_b64_v4i16((LAS v4i16_t*)p)); }
; DEV unsigned cvtpk(float lo, float hi) { typedef float f2 __attribute__((ext_vector_type(2))); typedef __bf16 b2 __attribute__((ext_vector_type(2))); f2 v = {lo, hi}; b2 b = __builtin_convertvector(v, b2); return __builtin_bit_cast(unsigned, b); }
; template <bool PV, bool WITHL>
; DEV void pv64(const LAS unsigned char* Vb, const AttnCtx& C, const ab8 (&pf)[2][2], f32x4 (&O)[2][4], f32x4 (&L)[2], bool a0, bool a1) {
;     if (PV) {
;         const int vr = 4 * C.q4 + (C.n >> 2), vc = (C.n & 3) >> 1, vs = 8 * (C.n & 1);
;         ab8 vf[4][2];
; #pragma unroll
;         for (int dt = 0; dt < 4; ++dt)
; #pragma unroll
;             for (int j = 0; j < 2; ++j) {
;                 const s16x4 lo = vtr(Vb + swz(32 * j + vr, 2 * dt + vc) + vs), hi = vtr(Vb + swz(32 * j + 16 + vr, 2 * dt + vc) + vs);
;                 vf[dt][j] = __builtin_shufflevector(lo, hi, 0, 1, 2, 3, 4, 5, 6, 7); }
;         __builtin_amdgcn_sched_barrier(0);
; #pragma unroll
;         for (int dt = 0; dt < 4; ++dt)
; #pragma unroll
;             for (int j = 0; j < 2; ++j) {
;                 if (a0) O[0][dt] = __builtin_amdgcn_mfma_f32_16x16x32_bf16(vf[dt][j], pf[0][j], O[0][dt], 0, 0, 0);
;                 if (a1) O[1][dt] = __builtin_amdgcn_mfma_f32_16x16x32_bf16(vf[dt][j], pf[1][j], O[1][dt], 0, 0, 0); }
; DEV void attn_unit_mfma(Frame& F, int qg, int kv) {
;     ...
;             for (int j = 0; j < 2; ++j) { v4u wv; wv.x = cvtpk(s[g][2 * j][0], s[g][2 * j][1]); wv.y = cvtpk(s[g][2 * j][2], s[g][2 * j][3]); wv.z = cvtpk(s[g][2 * j + 1][0], s[g][2 * j + 1][1]); wv.w = cvtpk(s[g][2 * j + 1][2], s[g][2 * j + 1][3]); pf[g][j] = __builtin_bit_cast(ab8, wv); } }
.LBB0_942:
	s_or_b64 exec, exec, s[10:11]
	v_subrev_u32_e32 v97, s24, v179
	v_subrev_u32_e32 v102, s24, v181
	v_subrev_u32_e32 v103, s24, v182
	v_subrev_u32_e32 v114, s24, v183
	v_subrev_u32_e32 v112, s24, v184
	v_subrev_u32_e32 v110, s24, v185
	v_subrev_u32_e32 v108, s24, v186
	v_subrev_u32_e32 v106, s24, v187
	v_subrev_u32_e32 v107, s24, v188
	v_subrev_u32_e32 v109, s24, v189
	v_subrev_u32_e32 v111, s24, v190
	v_subrev_u32_e32 v113, s24, v191
	v_subrev_u32_e32 v115, s24, v192
	v_subrev_u32_e32 v116, s24, v193
	v_subrev_u32_e32 v117, s24, v194
	v_subrev_u32_e32 v118, s24, v195
	v_cvt_pk_bf16_f32 v78, v78, v79
	v_cvt_pk_bf16_f32 v79, v80, v81
	v_cvt_pk_bf16_f32 v80, v74, v75
	v_cvt_pk_bf16_f32 v81, v76, v77
	v_cvt_pk_bf16_f32 v74, v86, v87
	v_cvt_pk_bf16_f32 v75, v88, v89
	v_cvt_pk_bf16_f32 v76, v82, v83
	v_cvt_pk_bf16_f32 v77, v84, v85
	v_cvt_pk_bf16_f32 v70, v70, v71
	v_cvt_pk_bf16_f32 v71, v72, v73
	v_cvt_pk_bf16_f32 v72, v66, v67
	v_cvt_pk_bf16_f32 v73, v68, v69
	v_cvt_pk_bf16_f32 v62, v62, v63
	v_cvt_pk_bf16_f32 v63, v64, v65
	v_cvt_pk_bf16_f32 v64, v58, v59
	v_cvt_pk_bf16_f32 v65, v60, v61
	v_add3_u32 v58, s14, v118, v180
	v_add3_u32 v60, s14, v117, v180
	v_add3_u32 v66, s14, v116, v180
	v_add3_u32 v68, s14, v115, v180
	v_add3_u32 v82, s14, v113, v180
	v_add3_u32 v84, s14, v111, v180
	v_add3_u32 v86, s14, v109, v180
	v_add3_u32 v88, s14, v107, v180
	v_add3_u32 v106, s14, v106, v180
	v_add3_u32 v108, s14, v108, v180
	v_add3_u32 v110, s14, v110, v180
	v_add3_u32 v112, s14, v112, v180
	v_add3_u32 v114, s14, v114, v180
	v_add3_u32 v103, s14, v103, v180
	v_add3_u32 v102, s14, v102, v180
	v_add3_u32 v97, s14, v97, v180
	ds_read_b64_tr_b16 v[58:59], v58
	ds_read_b64_tr_b16 v[60:61], v60
	ds_read_b64_tr_b16 v[66:67], v66
	ds_read_b64_tr_b16 v[68:69], v68
	ds_read_b64_tr_b16 v[82:83], v82
	ds_read_b64_tr_b16 v[84:85], v84
	ds_read_b64_tr_b16 v[86:87], v86
	ds_read_b64_tr_b16 v[88:89], v88
	ds_read_b64_tr_b16 v[106:107], v106
	ds_read_b64_tr_b16 v[116:117], v103
	ds_read_b64_tr_b16 v[118:119], v102
	ds_read_b64_tr_b16 v[120:121], v97
	ds_read_b64_tr_b16 v[108:109], v108
	ds_read_b64_tr_b16 v[110:111], v110
	ds_read_b64_tr_b16 v[112:113], v112
	ds_read_b64_tr_b16 v[114:115], v114
	s_waitcnt lgkmcnt(14)
	v_mfma_f32_16x16x32_bf16 v[54:57], v[58:61], v[74:77], v[54:57]
	s_addk_i32 s22, 0x400
	s_addk_i32 s14, 0x4000
	s_add_i32 s86, s86, 64
	v_mfma_f32_16x16x32_bf16 v[38:41], v[58:61], v[70:73], v[38:41]
	s_add_i32 s15, s15, 1
	s_add_i32 s12, s23, -1
	v_add_u32_e32 v96, 64, v96
	s_waitcnt lgkmcnt(10)
	v_mfma_f32_16x16x32_bf16 v[46:49], v[82:85], v[74:77], v[46:49]
	v_add_u32_e32 v104, 0xfffffc00, v104
	s_cmp_eq_u32 s12, s16
	v_mfma_f32_16x16x32_bf16 v[30:33], v[82:85], v[70:73], v[30:33]
	s_waitcnt lgkmcnt(3)
	v_mfma_f32_16x16x32_bf16 v[42:45], v[106:109], v[74:77], v[42:45]
	v_mfma_f32_16x16x32_bf16 v[26:29], v[106:109], v[70:73], v[26:29]
	s_waitcnt lgkmcnt(0)
	v_mfma_f32_16x16x32_bf16 v[50:53], v[114:117], v[74:77], v[50:53]
	v_mfma_f32_16x16x32_bf16 v[34:37], v[114:117], v[70:73], v[34:37]
	v_mfma_f32_16x16x32_bf16 v[54:57], v[66:69], v[78:81], v[54:57]
	v_mfma_f32_16x16x32_bf16 v[38:41], v[66:69], v[62:65], v[38:41]
	v_mfma_f32_16x16x32_bf16 v[46:49], v[86:89], v[78:81], v[46:49]
	v_mfma_f32_16x16x32_bf16 v[30:33], v[86:89], v[62:65], v[30:33]
	v_mfma_f32_16x16x32_bf16 v[42:45], v[110:113], v[78:81], v[42:45]
	v_mfma_f32_16x16x32_bf16 v[26:29], v[110:113], v[62:65], v[26:29]
	v_mfma_f32_16x16x32_bf16 v[50:53], v[118:121], v[78:81], v[50:53]
	v_mfma_f32_16x16x32_bf16 v[34:37], v[118:121], v[62:65], v[34:37]
	s_cbranch_scc1 .LBB0_969
	.p2align	6

; #define LAS __attribute__((address_space(3)))
; template <class Tp> DEV Tp* wsp(const Frame& F, size_t off) { return (Tp*)(F.ws + off); }
; #define RESET_STATE() do { _Pragma("unroll") for (int g = 0; g < 2; ++g) { m[g] = NEG_INF; L[g] = (f32x4){0.f, 0.f, 0.f, 0.f}; _Pragma("unroll") for (int dt = 0; dt < 4; ++dt) O[g][dt] = (f32x4){0.f, 0.f, 0.f, 0.f}; } } while (0)
; DEV void attn_unit_mfma(Frame& F, int qg, int kv) {
;     ...
;     RESET_STATE();
;     if (PROBE_REP & (1 << 20)) stream_tiles_multi<3>(F, nbl, wsp<bf16>(F, WS_KS) + kv * 64, wsp<bf16>(F, WS_VS) + kv * 64, [&](int i) { return 64 * lst[1 + i]; }, [&](int i, const LAS unsigned char* Kb, const LAS unsigned char* Vb) { (void)i; (void)Kb; (void)Vb; });
;     for (int rep_ = 0; rep_ < ((PROBE_REP >> 18) & 1) + 1; ++rep_) { RESET_STATE();
;     stream_stages_dma<3>(F, nbl, wsp<bf16>(F, WS_KS) + kv * 64, wsp<bf16>(F, WS_VS) + kv * 64, [&](int i) { return 64 * lst[1 + i]; }, [&](int i, const LAS unsigned char* Kb, const LAS unsigned char* Vb) {
;         const int j = lst[1 + i]; const unsigned byte = (msk[2 * j + (w >> 2)] >> (8 * (w & 3))) & 0xffu;
;         const bool a0 = (byte & 0xfu) != 0u, a1 = (byte & 0xf0u) != 0u;
;         if (a0 || a1) {
;             const bool near = j >= cur - 2; const float bi = near ? 0.f : C.b31;
;             const bool c0 = ((byte >> (C.n >> 2)) & 1u) != 0u, c1 = ((byte >> (4 + (C.n >> 2))) & 1u) != 0u;
.LBB0_1166:
	v_cmp_lt_i32_e32 vcc, v147, v205
	v_mov_b32_e32 v28, v19
	v_mov_b32_e32 v29, v19
	v_cndmask_b32_e32 v26, v139, v147, vcc
	v_cmp_lt_i32_e32 vcc, v145, v205
	v_lshlrev_b32_e32 v210, 2, v26
	v_mov_b32_e32 v27, v19
	v_cndmask_b32_e32 v26, v139, v145, vcc
	v_lshlrev_b32_e32 v211, 2, v26
	v_mov_b32_e32 v26, v19
	v_mov_b64_e32 v[32:33], v[28:29]
	v_mov_b64_e32 v[36:37], v[28:29]
	v_mov_b64_e32 v[40:41], v[28:29]
	v_mov_b64_e32 v[48:49], v[28:29]
	v_mov_b64_e32 v[52:53], v[28:29]
	v_mov_b64_e32 v[56:57], v[28:29]
	v_mov_b64_e32 v[64:65], v[28:29]
	v_mov_b64_e32 v[44:45], v[28:29]
	v_mov_b64_e32 v[60:61], v[28:29]
	v_lshlrev_b32_e64 v206, v196, 1
	v_lshlrev_b32_e64 v207, v196, 16
	v_not_b32_e32 v208, v20
	s_mov_b32 s28, 2
	v_or_b32_e32 v1, 3, v20
	v_or_b32_e32 v158, 2, v20
	v_lshlrev_b32_e32 v209, 7, v94
	s_mov_b32 s8, 0
	v_mov_b32_e32 v213, 0xff800000
	v_mov_b64_e32 v[30:31], v[26:27]
	v_mov_b64_e32 v[34:35], v[26:27]
	v_mov_b64_e32 v[38:39], v[26:27]
	v_mov_b64_e32 v[46:47], v[26:27]
	v_mov_b64_e32 v[50:51], v[26:27]
	v_mov_b64_e32 v[54:55], v[26:27]
	v_mov_b64_e32 v[62:63], v[26:27]
	v_mov_b64_e32 v[42:43], v[26:27]
	v_mov_b64_e32 v[58:59], v[26:27]
	v_mov_b32_e32 v212, 0xff800000
	v_mov_b32_e32 v66, s24
	ds_read_b32 v67, v66
	ds_read_b32 v68, v66 offset:4
	ds_read_b32 v69, v66 offset:8
	ds_read_b32 v73, v66 offset:12
	ds_read_b32 v74, v66 offset:16
	ds_read_b32 v75, v66 offset:20
	s_waitcnt lgkmcnt(0)
	v_lshl_add_u32 v70, v67, 3, s2
	v_lshl_add_u32 v71, v68, 3, s2
	v_lshl_add_u32 v72, v69, 3, s2
	ds_read_b32 v70, v70
	ds_read_b32 v71, v71
	ds_read_b32 v72, v72
	v_readfirstlane_b32 s98, v67
	v_readfirstlane_b32 s99, v68
	v_readfirstlane_b32 s100, v69
	v_readfirstlane_b32 s37, v73
	v_readfirstlane_b32 s38, v74
	v_readfirstlane_b32 s39, v75
	s_waitcnt lgkmcnt(0)
	v_readfirstlane_b32 s9, v70
	v_readfirstlane_b32 s10, v71
	v_readfirstlane_b32 s11, v72
	s_and_b32 s98, s98, 0xffff
	s_and_b32 s99, s99, 0xffff
	s_and_b32 s100, s100, 0xffff
	s_lshr_b32 s9, s9, s33
	s_and_b32 s9, s9, 0xff
	s_lshl_b32 s9, s9, 16
	s_or_b32 s98, s98, s9
	s_lshr_b32 s10, s10, s33
	s_and_b32 s10, s10, 0xff
	s_lshl_b32 s10, s10, 16
	s_or_b32 s99, s99, s10
	s_lshr_b32 s11, s11, s33
	s_and_b32 s11, s11, 0xff
	s_lshl_b32 s11, s11, 16
	s_or_b32 s100, s100, s11
	.p2align	6

; DEV unsigned cvtpk(float lo, float hi) { typedef float f2 __attribute__((ext_vector_type(2))); typedef __bf16 b2 __attribute__((ext_vector_type(2))); f2 v = {lo, hi}; b2 b = __builtin_convertvector(v, b2); return __builtin_bit_cast(unsigned, b); }
; DEV void ref_step(f32x4 (&s)[4], float& m, f32x4 (&O)[4], f32x4& L, ab8 (&pf)[2], bool colact) {
;     ...
; #pragma unroll
;     for (int kt = 0; kt < 4; ++kt)
; #pragma unroll
;         for (int i = 0; i < 4; ++i) s[kt][i] = __builtin_amdgcn_exp2f(s[kt][i]);
; #pragma unroll
;     for (int j = 0; j < 2; ++j) { v4u w; w.x = cvtpk(s[2 * j][0], s[2 * j][1]); w.y = cvtpk(s[2 * j][2], s[2 * j][3]); w.z = cvtpk(s[2 * j + 1][0], s[2 * j + 1][1]); w.w = cvtpk(s[2 * j + 1][2], s[2 * j + 1][3]); pf[j] = __builtin_bit_cast(ab8, w); }
; DEV void pv_mma(const AttnCtx& C, const ab8 (&vf)[4][2], const ab8 (&pf)[2][2], f32x4 (&O)[2][4], f32x4 (&L)[2], bool a0, bool a1) {
; #pragma unroll
;     for (int dt = 0; dt < 4; ++dt)
; #pragma unroll
;         for (int j = 0; j < 2; ++j) {
;             if (a0) O[0][dt] = __builtin_amdgcn_mfma_f32_16x16x32_bf16(vf[dt][j], pf[0][j], O[0][dt], 0, 0, 0);
;             if (a1) O[1][dt] = __builtin_amdgcn_mfma_f32_16x16x32_bf16(vf[dt][j], pf[1][j], O[1][dt], 0, 0, 0); }
;     const short one = (C.n == 0) ? (short)0x3F80 : (short)0; const ab8 ones = {one, one, one, one, one, one, one, one};
; #pragma unroll
;     for (int j = 0; j < 2; ++j) {
;         if (a0) L[0] = __builtin_amdgcn_mfma_f32_16x16x32_bf16(ones, pf[0][j], L[0], 0, 0, 0);
;         if (a1) L[1] = __builtin_amdgcn_mfma_f32_16x16x32_bf16(ones, pf[1][j], L[1], 0, 0, 0); }
.LBB0_1265:
	v_exp_f32_e32 v98, v158
	v_exp_f32_e32 v99, v196
	v_exp_f32_e32 v100, v197
	v_exp_f32_e32 v101, v198
	v_exp_f32_e32 v102, v199
	v_exp_f32_e32 v103, v200
	v_exp_f32_e32 v104, v201
	v_exp_f32_e32 v105, v202
	v_cvt_pk_bf16_f32 v98, v98, v99
	v_cvt_pk_bf16_f32 v99, v100, v101
	v_cvt_pk_bf16_f32 v100, v102, v103
	v_cvt_pk_bf16_f32 v101, v104, v105
	v_exp_f32_e32 v102, v136
	v_exp_f32_e32 v103, v137
	v_exp_f32_e32 v104, v144
	v_exp_f32_e32 v105, v145
	v_exp_f32_e32 v106, v146
	v_exp_f32_e32 v107, v147
	v_exp_f32_e32 v108, v156
	v_exp_f32_e32 v109, v157
	v_cvt_pk_bf16_f32 v102, v102, v103
	v_cvt_pk_bf16_f32 v103, v104, v105
	v_cvt_pk_bf16_f32 v104, v106, v107
	v_cvt_pk_bf16_f32 v105, v108, v109
	v_exp_f32_e32 v106, v114
	v_exp_f32_e32 v107, v115
	v_exp_f32_e32 v108, v116
	v_exp_f32_e32 v109, v117
	v_exp_f32_e32 v110, v120
	v_exp_f32_e32 v111, v121
	v_exp_f32_e32 v112, v118
	v_exp_f32_e32 v113, v119
	v_cvt_pk_bf16_f32 v106, v106, v107
	v_cvt_pk_bf16_f32 v107, v108, v109
	v_cvt_pk_bf16_f32 v108, v110, v111
	v_cvt_pk_bf16_f32 v109, v112, v113
	v_exp_f32_e32 v114, v124
	v_exp_f32_e32 v115, v125
	v_exp_f32_e32 v116, v126
	v_exp_f32_e32 v117, v127
	v_exp_f32_e32 v118, v128
	v_exp_f32_e32 v119, v129
	s_waitcnt lgkmcnt(0)
	v_mfma_f32_16x16x32_bf16 v[58:61], v[66:69], v[102:105], v[58:61]
	v_exp_f32_e32 v110, v123
	s_add_i32 s41, s41, 1
	s_add_i32 s43, s43, 1
	v_mfma_f32_16x16x32_bf16 v[38:41], v[66:69], v[106:109], v[38:41]
	v_exp_f32_e32 v69, v122
	v_cvt_pk_bf16_f32 v66, v114, v115
	v_cvt_pk_bf16_f32 v67, v116, v117
	v_mfma_f32_16x16x32_bf16 v[54:57], v[74:77], v[102:105], v[54:57]
	v_cvt_pk_bf16_f32 v68, v118, v119
	v_cvt_pk_bf16_f32 v69, v69, v110
	s_add_i32 s24, s38, s41
	v_mfma_f32_16x16x32_bf16 v[34:37], v[74:77], v[106:109], v[34:37]
	s_addk_i32 s42, 0x4000
	s_add_i32 s40, s40, -1
	s_add_i32 s34, s34, 64
	v_mfma_f32_16x16x32_bf16 v[50:53], v[82:85], v[102:105], v[50:53]
	v_subrev_u32_e32 v133, 64, v133
	s_cmp_eq_u32 s24, 14
	v_mfma_f32_16x16x32_bf16 v[30:33], v[82:85], v[106:109], v[30:33]
	v_mfma_f32_16x16x32_bf16 v[46:49], v[90:93], v[102:105], v[46:49]
	v_mfma_f32_16x16x32_bf16 v[26:29], v[90:93], v[106:109], v[26:29]
	v_mfma_f32_16x16x32_bf16 v[62:65], v[22:25], v[102:105], v[62:65]
	v_mfma_f32_16x16x32_bf16 v[42:45], v[22:25], v[106:109], v[42:45]
	v_mfma_f32_16x16x32_bf16 v[58:61], v[70:73], v[98:101], v[58:61]
	v_mfma_f32_16x16x32_bf16 v[38:41], v[70:73], v[66:69], v[38:41]
	v_mfma_f32_16x16x32_bf16 v[54:57], v[78:81], v[98:101], v[54:57]
	v_mfma_f32_16x16x32_bf16 v[34:37], v[78:81], v[66:69], v[34:37]
	v_mfma_f32_16x16x32_bf16 v[50:53], v[86:89], v[98:101], v[50:53]
	v_mfma_f32_16x16x32_bf16 v[30:33], v[86:89], v[66:69], v[30:33]
	v_mfma_f32_16x16x32_bf16 v[46:49], v[94:97], v[98:101], v[46:49]
	v_mfma_f32_16x16x32_bf16 v[26:29], v[94:97], v[66:69], v[26:29]
	v_mfma_f32_16x16x32_bf16 v[62:65], v[22:25], v[98:101], v[62:65]
	v_mfma_f32_16x16x32_bf16 v[42:45], v[22:25], v[66:69], v[42:45]
	s_cbranch_scc1 .LBB0_1299
	.p2align	6

; template <class Epi, class Sched, bool ALIGN_EPI = false, bool SP2 = false>
; __device__ __forceinline__ void gemm_phase(PG8_LAS unsigned char* lds, const int Kdim, const Sched& S, const Epi& E) {
;     ...
; #pragma unroll
;         for (int a = 0; a < 2; ++a)
; #pragma unroll
;             for (int b = 0; b < 2; ++b)
; #pragma unroll
;                 for (int m = 0; m < 4; ++m)
; #pragma unroll
;                     for (int n = 0; n < 2; ++n) acc[a][b][m][n] = (f32x4){0.f, 0.f, 0.f, 0.f};
;         cur = nxt; cA = nA; cB = nB; ++ui;
.LBB0_1780:
	s_add_u32 s26, s26, 0x20080
	s_addc_u32 s27, s27, 0
	s_add_u32 s17, s28, 0x100
	v_mov_b32_e32 v2, 0
	s_addc_u32 s19, s29, 0
	s_mov_b32 s23, -2
	v_mov_b32_e32 v3, v2
	v_mov_b32_e32 v4, v2
	v_mov_b32_e32 v5, v2
	v_mov_b32_e32 v6, v2
	v_mov_b32_e32 v7, v2
	v_mov_b32_e32 v8, v2
	v_mov_b32_e32 v9, v2
	v_mov_b32_e32 v18, v2
	v_mov_b32_e32 v19, v2
	v_mov_b32_e32 v20, v2
	v_mov_b32_e32 v21, v2
	v_mov_b32_e32 v22, v2
	v_mov_b32_e32 v23, v2
	v_mov_b32_e32 v24, v2
	v_mov_b32_e32 v25, v2
	v_mov_b32_e32 v34, v2
	v_mov_b32_e32 v35, v2
	v_mov_b32_e32 v36, v2
	v_mov_b32_e32 v37, v2
	v_mov_b32_e32 v38, v2
	v_mov_b32_e32 v39, v2
	v_mov_b32_e32 v40, v2
	v_mov_b32_e32 v41, v2
	v_mov_b32_e32 v50, v2
	v_mov_b32_e32 v51, v2
	v_mov_b32_e32 v52, v2
	v_mov_b32_e32 v53, v2
	v_mov_b32_e32 v54, v2
	v_mov_b32_e32 v55, v2
	v_mov_b32_e32 v56, v2
	v_mov_b32_e32 v57, v2
	v_mov_b32_e32 v10, v2
	v_mov_b32_e32 v11, v2
	v_mov_b32_e32 v12, v2
	v_mov_b32_e32 v13, v2
	v_mov_b32_e32 v14, v2
	v_mov_b32_e32 v15, v2
	v_mov_b32_e32 v16, v2
	v_mov_b32_e32 v17, v2
	v_mov_b32_e32 v26, v2
	v_mov_b32_e32 v27, v2
	v_mov_b32_e32 v28, v2
	v_mov_b32_e32 v29, v2
	v_mov_b32_e32 v30, v2
	v_mov_b32_e32 v31, v2
	v_mov_b32_e32 v32, v2
	v_mov_b32_e32 v33, v2
	v_mov_b32_e32 v42, v2
	v_mov_b32_e32 v43, v2
	v_mov_b32_e32 v44, v2
	v_mov_b32_e32 v45, v2
	v_mov_b32_e32 v46, v2
	v_mov_b32_e32 v47, v2
	v_mov_b32_e32 v48, v2
	v_mov_b32_e32 v49, v2
	v_mov_b32_e32 v58, v2
	v_mov_b32_e32 v59, v2
	v_mov_b32_e32 v60, v2
	v_mov_b32_e32 v61, v2
	v_mov_b32_e32 v62, v2
	v_mov_b32_e32 v63, v2
	v_mov_b32_e32 v64, v2
	v_mov_b32_e32 v65, v2
	v_mov_b32_e32 v66, v2
	v_mov_b32_e32 v67, v2
	v_mov_b32_e32 v68, v2
	v_mov_b32_e32 v69, v2
	v_mov_b32_e32 v70, v2
	v_mov_b32_e32 v71, v2
	v_mov_b32_e32 v72, v2
	v_mov_b32_e32 v73, v2
	v_mov_b32_e32 v82, v2
	v_mov_b32_e32 v83, v2
	v_mov_b32_e32 v84, v2
	v_mov_b32_e32 v85, v2
	v_mov_b32_e32 v86, v2
	v_mov_b32_e32 v87, v2
	v_mov_b32_e32 v88, v2
	v_mov_b32_e32 v89, v2
	v_mov_b32_e32 v98, v2
	v_mov_b32_e32 v99, v2
	v_mov_b32_e32 v100, v2
	v_mov_b32_e32 v101, v2
	v_mov_b32_e32 v102, v2
	v_mov_b32_e32 v103, v2
	v_mov_b32_e32 v104, v2
	v_mov_b32_e32 v105, v2
	v_mov_b32_e32 v114, v2
	v_mov_b32_e32 v115, v2
	v_mov_b32_e32 v116, v2
	v_mov_b32_e32 v117, v2
	v_mov_b32_e32 v118, v2
	v_mov_b32_e32 v119, v2
	v_mov_b32_e32 v120, v2
	v_mov_b32_e32 v121, v2
	v_mov_b32_e32 v74, v2
	v_mov_b32_e32 v75, v2
	v_mov_b32_e32 v76, v2
	v_mov_b32_e32 v77, v2
	v_mov_b32_e32 v78, v2
	v_mov_b32_e32 v79, v2
	v_mov_b32_e32 v80, v2
	v_mov_b32_e32 v81, v2
	v_mov_b32_e32 v90, v2
	v_mov_b32_e32 v91, v2
	v_mov_b32_e32 v92, v2
	v_mov_b32_e32 v93, v2
	v_mov_b32_e32 v94, v2
	v_mov_b32_e32 v95, v2
	v_mov_b32_e32 v96, v2
	v_mov_b32_e32 v97, v2
	v_mov_b32_e32 v106, v2
	v_mov_b32_e32 v107, v2
	v_mov_b32_e32 v108, v2
	v_mov_b32_e32 v109, v2
	v_mov_b32_e32 v110, v2
	v_mov_b32_e32 v111, v2
	v_mov_b32_e32 v112, v2
	v_mov_b32_e32 v113, v2
	v_mov_b32_e32 v122, v2
	v_mov_b32_e32 v123, v2
	v_mov_b32_e32 v124, v2
	v_mov_b32_e32 v125, v2
	v_mov_b32_e32 v126, v2
	v_mov_b32_e32 v127, v2
	v_mov_b32_e32 v128, v2
	v_mov_b32_e32 v129, v2
	.p2align	6

; template <class Epi, class Sched, bool ALIGN_EPI = false, bool SP2 = false>
; __device__ __forceinline__ void gemm_phase(PG8_LAS unsigned char* lds, const int Kdim, const Sched& S, const Epi& E) {
;     ...
; #pragma unroll
;         for (int a = 0; a < 2; ++a)
; #pragma unroll
;             for (int b = 0; b < 2; ++b)
; #pragma unroll
;                 for (int m = 0; m < 4; ++m)
; #pragma unroll
;                     for (int n = 0; n < 2; ++n) acc[a][b][m][n] = (f32x4){0.f, 0.f, 0.f, 0.f};
;         cur = nxt; cA = nA; cB = nB; ++ui;
.LBB0_1832:
	s_add_u32 s28, s28, 0x20080
	s_addc_u32 s29, s29, 0
	s_add_u32 s19, s30, 0x100
	v_mov_b32_e32 v2, 0
	s_addc_u32 s21, s31, 0
	s_mov_b32 s25, -2
	v_mov_b32_e32 v3, v2
	v_mov_b32_e32 v4, v2
	v_mov_b32_e32 v5, v2
	v_mov_b32_e32 v6, v2
	v_mov_b32_e32 v7, v2
	v_mov_b32_e32 v8, v2
	v_mov_b32_e32 v9, v2
	v_mov_b32_e32 v18, v2
	v_mov_b32_e32 v19, v2
	v_mov_b32_e32 v20, v2
	v_mov_b32_e32 v21, v2
	v_mov_b32_e32 v22, v2
	v_mov_b32_e32 v23, v2
	v_mov_b32_e32 v24, v2
	v_mov_b32_e32 v25, v2
	v_mov_b32_e32 v34, v2
	v_mov_b32_e32 v35, v2
	v_mov_b32_e32 v36, v2
	v_mov_b32_e32 v37, v2
	v_mov_b32_e32 v38, v2
	v_mov_b32_e32 v39, v2
	v_mov_b32_e32 v40, v2
	v_mov_b32_e32 v41, v2
	v_mov_b32_e32 v50, v2
	v_mov_b32_e32 v51, v2
	v_mov_b32_e32 v52, v2
	v_mov_b32_e32 v53, v2
	v_mov_b32_e32 v54, v2
	v_mov_b32_e32 v55, v2
	v_mov_b32_e32 v56, v2
	v_mov_b32_e32 v57, v2
	v_mov_b32_e32 v10, v2
	v_mov_b32_e32 v11, v2
	v_mov_b32_e32 v12, v2
	v_mov_b32_e32 v13, v2
	v_mov_b32_e32 v14, v2
	v_mov_b32_e32 v15, v2
	v_mov_b32_e32 v16, v2
	v_mov_b32_e32 v17, v2
	v_mov_b32_e32 v26, v2
	v_mov_b32_e32 v27, v2
	v_mov_b32_e32 v28, v2
	v_mov_b32_e32 v29, v2
	v_mov_b32_e32 v30, v2
	v_mov_b32_e32 v31, v2
	v_mov_b32_e32 v32, v2
	v_mov_b32_e32 v33, v2
	v_mov_b32_e32 v42, v2
	v_mov_b32_e32 v43, v2
	v_mov_b32_e32 v44, v2
	v_mov_b32_e32 v45, v2
	v_mov_b32_e32 v46, v2
	v_mov_b32_e32 v47, v2
	v_mov_b32_e32 v48, v2
	v_mov_b32_e32 v49, v2
	v_mov_b32_e32 v58, v2
	v_mov_b32_e32 v59, v2
	v_mov_b32_e32 v60, v2
	v_mov_b32_e32 v61, v2
	v_mov_b32_e32 v62, v2
	v_mov_b32_e32 v63, v2
	v_mov_b32_e32 v64, v2
	v_mov_b32_e32 v65, v2
	v_mov_b32_e32 v66, v2
	v_mov_b32_e32 v67, v2
	v_mov_b32_e32 v68, v2
	v_mov_b32_e32 v69, v2
	v_mov_b32_e32 v70, v2
	v_mov_b32_e32 v71, v2
	v_mov_b32_e32 v72, v2
	v_mov_b32_e32 v73, v2
	v_mov_b32_e32 v82, v2
	v_mov_b32_e32 v83, v2
	v_mov_b32_e32 v84, v2
	v_mov_b32_e32 v85, v2
	v_mov_b32_e32 v86, v2
	v_mov_b32_e32 v87, v2
	v_mov_b32_e32 v88, v2
	v_mov_b32_e32 v89, v2
	v_mov_b32_e32 v98, v2
	v_mov_b32_e32 v99, v2
	v_mov_b32_e32 v100, v2
	v_mov_b32_e32 v101, v2
	v_mov_b32_e32 v102, v2
	v_mov_b32_e32 v103, v2
	v_mov_b32_e32 v104, v2
	v_mov_b32_e32 v105, v2
	v_mov_b32_e32 v114, v2
	v_mov_b32_e32 v115, v2
	v_mov_b32_e32 v116, v2
	v_mov_b32_e32 v117, v2
	v_mov_b32_e32 v118, v2
	v_mov_b32_e32 v119, v2
	v_mov_b32_e32 v120, v2
	v_mov_b32_e32 v121, v2
	v_mov_b32_e32 v74, v2
	v_mov_b32_e32 v75, v2
	v_mov_b32_e32 v76, v2
	v_mov_b32_e32 v77, v2
	v_mov_b32_e32 v78, v2
	v_mov_b32_e32 v79, v2
	v_mov_b32_e32 v80, v2
	v_mov_b32_e32 v81, v2
	v_mov_b32_e32 v90, v2
	v_mov_b32_e32 v91, v2
	v_mov_b32_e32 v92, v2
	v_mov_b32_e32 v93, v2
	v_mov_b32_e32 v94, v2
	v_mov_b32_e32 v95, v2
	v_mov_b32_e32 v96, v2
	v_mov_b32_e32 v97, v2
	v_mov_b32_e32 v106, v2
	v_mov_b32_e32 v107, v2
	v_mov_b32_e32 v108, v2
	v_mov_b32_e32 v109, v2
	v_mov_b32_e32 v110, v2
	v_mov_b32_e32 v111, v2
	v_mov_b32_e32 v112, v2
	v_mov_b32_e32 v113, v2
	v_mov_b32_e32 v122, v2
	v_mov_b32_e32 v123, v2
	v_mov_b32_e32 v124, v2
	v_mov_b32_e32 v125, v2
	v_mov_b32_e32 v126, v2
	v_mov_b32_e32 v127, v2
	v_mov_b32_e32 v128, v2
	v_mov_b32_e32 v129, v2
	.p2align	6

; template <class Epi, class Sched, bool ALIGN_EPI = false, bool SP2 = false>
; __device__ __forceinline__ void gemm_phase(PG8_LAS unsigned char* lds, const int Kdim, const Sched& S, const Epi& E) {
;     ...
; #pragma unroll
;         for (int a = 0; a < 2; ++a)
; #pragma unroll
;             for (int b = 0; b < 2; ++b)
; #pragma unroll
;                 for (int m = 0; m < 4; ++m)
; #pragma unroll
;                     for (int n = 0; n < 2; ++n) acc[a][b][m][n] = (f32x4){0.f, 0.f, 0.f, 0.f};
;         cur = nxt; cA = nA; cB = nB; ++ui;
.LBB0_1936:
	s_add_u32 s26, s26, 0x40080
	s_addc_u32 s27, s27, 0
	s_add_u32 s17, s28, 0x100
	v_mov_b32_e32 v2, 0
	s_addc_u32 s19, s29, 0
	s_mov_b32 s23, -2
	v_mov_b32_e32 v3, v2
	v_mov_b32_e32 v4, v2
	v_mov_b32_e32 v5, v2
	v_mov_b32_e32 v6, v2
	v_mov_b32_e32 v7, v2
	v_mov_b32_e32 v8, v2
	v_mov_b32_e32 v9, v2
	v_mov_b32_e32 v18, v2
	v_mov_b32_e32 v19, v2
	v_mov_b32_e32 v20, v2
	v_mov_b32_e32 v21, v2
	v_mov_b32_e32 v22, v2
	v_mov_b32_e32 v23, v2
	v_mov_b32_e32 v24, v2
	v_mov_b32_e32 v25, v2
	v_mov_b32_e32 v34, v2
	v_mov_b32_e32 v35, v2
	v_mov_b32_e32 v36, v2
	v_mov_b32_e32 v37, v2
	v_mov_b32_e32 v38, v2
	v_mov_b32_e32 v39, v2
	v_mov_b32_e32 v40, v2
	v_mov_b32_e32 v41, v2
	v_mov_b32_e32 v50, v2
	v_mov_b32_e32 v51, v2
	v_mov_b32_e32 v52, v2
	v_mov_b32_e32 v53, v2
	v_mov_b32_e32 v54, v2
	v_mov_b32_e32 v55, v2
	v_mov_b32_e32 v56, v2
	v_mov_b32_e32 v57, v2
	v_mov_b32_e32 v10, v2
	v_mov_b32_e32 v11, v2
	v_mov_b32_e32 v12, v2
	v_mov_b32_e32 v13, v2
	v_mov_b32_e32 v14, v2
	v_mov_b32_e32 v15, v2
	v_mov_b32_e32 v16, v2
	v_mov_b32_e32 v17, v2
	v_mov_b32_e32 v26, v2
	v_mov_b32_e32 v27, v2
	v_mov_b32_e32 v28, v2
	v_mov_b32_e32 v29, v2
	v_mov_b32_e32 v30, v2
	v_mov_b32_e32 v31, v2
	v_mov_b32_e32 v32, v2
	v_mov_b32_e32 v33, v2
	v_mov_b32_e32 v42, v2
	v_mov_b32_e32 v43, v2
	v_mov_b32_e32 v44, v2
	v_mov_b32_e32 v45, v2
	v_mov_b32_e32 v46, v2
	v_mov_b32_e32 v47, v2
	v_mov_b32_e32 v48, v2
	v_mov_b32_e32 v49, v2
	v_mov_b32_e32 v58, v2
	v_mov_b32_e32 v59, v2
	v_mov_b32_e32 v60, v2
	v_mov_b32_e32 v61, v2
	v_mov_b32_e32 v62, v2
	v_mov_b32_e32 v63, v2
	v_mov_b32_e32 v64, v2
	v_mov_b32_e32 v65, v2
	v_mov_b32_e32 v66, v2
	v_mov_b32_e32 v67, v2
	v_mov_b32_e32 v68, v2
	v_mov_b32_e32 v69, v2
	v_mov_b32_e32 v70, v2
	v_mov_b32_e32 v71, v2
	v_mov_b32_e32 v72, v2
	v_mov_b32_e32 v73, v2
	v_mov_b32_e32 v82, v2
	v_mov_b32_e32 v83, v2
	v_mov_b32_e32 v84, v2
	v_mov_b32_e32 v85, v2
	v_mov_b32_e32 v86, v2
	v_mov_b32_e32 v87, v2
	v_mov_b32_e32 v88, v2
	v_mov_b32_e32 v89, v2
	v_mov_b32_e32 v98, v2
	v_mov_b32_e32 v99, v2
	v_mov_b32_e32 v100, v2
	v_mov_b32_e32 v101, v2
	v_mov_b32_e32 v102, v2
	v_mov_b32_e32 v103, v2
	v_mov_b32_e32 v104, v2
	v_mov_b32_e32 v105, v2
	v_mov_b32_e32 v114, v2
	v_mov_b32_e32 v115, v2
	v_mov_b32_e32 v116, v2
	v_mov_b32_e32 v117, v2
	v_mov_b32_e32 v118, v2
	v_mov_b32_e32 v119, v2
	v_mov_b32_e32 v120, v2
	v_mov_b32_e32 v121, v2
	v_mov_b32_e32 v74, v2
	v_mov_b32_e32 v75, v2
	v_mov_b32_e32 v76, v2
	v_mov_b32_e32 v77, v2
	v_mov_b32_e32 v78, v2
	v_mov_b32_e32 v79, v2
	v_mov_b32_e32 v80, v2
	v_mov_b32_e32 v81, v2
	v_mov_b32_e32 v90, v2
	v_mov_b32_e32 v91, v2
	v_mov_b32_e32 v92, v2
	v_mov_b32_e32 v93, v2
	v_mov_b32_e32 v94, v2
	v_mov_b32_e32 v95, v2
	v_mov_b32_e32 v96, v2
	v_mov_b32_e32 v97, v2
	v_mov_b32_e32 v106, v2
	v_mov_b32_e32 v107, v2
	v_mov_b32_e32 v108, v2
	v_mov_b32_e32 v109, v2
	v_mov_b32_e32 v110, v2
	v_mov_b32_e32 v111, v2
	v_mov_b32_e32 v112, v2
	v_mov_b32_e32 v113, v2
	v_mov_b32_e32 v122, v2
	v_mov_b32_e32 v123, v2
	v_mov_b32_e32 v124, v2
	v_mov_b32_e32 v125, v2
	v_mov_b32_e32 v126, v2
	v_mov_b32_e32 v127, v2
	v_mov_b32_e32 v128, v2
	v_mov_b32_e32 v129, v2
	.p2align	6

; template <class Epi, class Sched, bool ALIGN_EPI = false, bool SP2 = false>
; __device__ __forceinline__ void gemm_phase(PG8_LAS unsigned char* lds, const int Kdim, const Sched& S, const Epi& E) {
;     ...
; #pragma unroll
;         for (int a = 0; a < 2; ++a)
; #pragma unroll
;             for (int b = 0; b < 2; ++b)
; #pragma unroll
;                 for (int m = 0; m < 4; ++m)
; #pragma unroll
;                     for (int n = 0; n < 2; ++n) acc[a][b][m][n] = (f32x4){0.f, 0.f, 0.f, 0.f};
;         cur = nxt; cA = nA; cB = nB; ++ui;
.LBB0_2097:
	s_add_u32 s24, s24, 0x40080
	s_addc_u32 s25, s25, 0
	s_add_u32 s15, s26, 0x100
	v_mov_b32_e32 v2, 0
	s_addc_u32 s17, s27, 0
	s_mov_b32 s21, -2
	v_mov_b32_e32 v3, v2
	v_mov_b32_e32 v4, v2
	v_mov_b32_e32 v5, v2
	v_mov_b32_e32 v6, v2
	v_mov_b32_e32 v7, v2
	v_mov_b32_e32 v8, v2
	v_mov_b32_e32 v9, v2
	v_mov_b32_e32 v18, v2
	v_mov_b32_e32 v19, v2
	v_mov_b32_e32 v20, v2
	v_mov_b32_e32 v21, v2
	v_mov_b32_e32 v22, v2
	v_mov_b32_e32 v23, v2
	v_mov_b32_e32 v24, v2
	v_mov_b32_e32 v25, v2
	v_mov_b32_e32 v34, v2
	v_mov_b32_e32 v35, v2
	v_mov_b32_e32 v36, v2
	v_mov_b32_e32 v37, v2
	v_mov_b32_e32 v38, v2
	v_mov_b32_e32 v39, v2
	v_mov_b32_e32 v40, v2
	v_mov_b32_e32 v41, v2
	v_mov_b32_e32 v50, v2
	v_mov_b32_e32 v51, v2
	v_mov_b32_e32 v52, v2
	v_mov_b32_e32 v53, v2
	v_mov_b32_e32 v54, v2
	v_mov_b32_e32 v55, v2
	v_mov_b32_e32 v56, v2
	v_mov_b32_e32 v57, v2
	v_mov_b32_e32 v10, v2
	v_mov_b32_e32 v11, v2
	v_mov_b32_e32 v12, v2
	v_mov_b32_e32 v13, v2
	v_mov_b32_e32 v14, v2
	v_mov_b32_e32 v15, v2
	v_mov_b32_e32 v16, v2
	v_mov_b32_e32 v17, v2
	v_mov_b32_e32 v26, v2
	v_mov_b32_e32 v27, v2
	v_mov_b32_e32 v28, v2
	v_mov_b32_e32 v29, v2
	v_mov_b32_e32 v30, v2
	v_mov_b32_e32 v31, v2
	v_mov_b32_e32 v32, v2
	v_mov_b32_e32 v33, v2
	v_mov_b32_e32 v42, v2
	v_mov_b32_e32 v43, v2
	v_mov_b32_e32 v44, v2
	v_mov_b32_e32 v45, v2
	v_mov_b32_e32 v46, v2
	v_mov_b32_e32 v47, v2
	v_mov_b32_e32 v48, v2
	v_mov_b32_e32 v49, v2
	v_mov_b32_e32 v58, v2
	v_mov_b32_e32 v59, v2
	v_mov_b32_e32 v60, v2
	v_mov_b32_e32 v61, v2
	v_mov_b32_e32 v62, v2
	v_mov_b32_e32 v63, v2
	v_mov_b32_e32 v64, v2
	v_mov_b32_e32 v65, v2
	v_mov_b32_e32 v66, v2
	v_mov_b32_e32 v67, v2
	v_mov_b32_e32 v68, v2
	v_mov_b32_e32 v69, v2
	v_mov_b32_e32 v70, v2
	v_mov_b32_e32 v71, v2
	v_mov_b32_e32 v72, v2
	v_mov_b32_e32 v73, v2
	v_mov_b32_e32 v82, v2
	v_mov_b32_e32 v83, v2
	v_mov_b32_e32 v84, v2
	v_mov_b32_e32 v85, v2
	v_mov_b32_e32 v86, v2
	v_mov_b32_e32 v87, v2
	v_mov_b32_e32 v88, v2
	v_mov_b32_e32 v89, v2
	v_mov_b32_e32 v98, v2
	v_mov_b32_e32 v99, v2
	v_mov_b32_e32 v100, v2
	v_mov_b32_e32 v101, v2
	v_mov_b32_e32 v102, v2
	v_mov_b32_e32 v103, v2
	v_mov_b32_e32 v104, v2
	v_mov_b32_e32 v105, v2
	v_mov_b32_e32 v114, v2
	v_mov_b32_e32 v115, v2
	v_mov_b32_e32 v116, v2
	v_mov_b32_e32 v117, v2
	v_mov_b32_e32 v118, v2
	v_mov_b32_e32 v119, v2
	v_mov_b32_e32 v120, v2
	v_mov_b32_e32 v121, v2
	v_mov_b32_e32 v74, v2
	v_mov_b32_e32 v75, v2
	v_mov_b32_e32 v76, v2
	v_mov_b32_e32 v77, v2
	v_mov_b32_e32 v78, v2
	v_mov_b32_e32 v79, v2
	v_mov_b32_e32 v80, v2
	v_mov_b32_e32 v81, v2
	v_mov_b32_e32 v90, v2
	v_mov_b32_e32 v91, v2
	v_mov_b32_e32 v92, v2
	v_mov_b32_e32 v93, v2
	v_mov_b32_e32 v94, v2
	v_mov_b32_e32 v95, v2
	v_mov_b32_e32 v96, v2
	v_mov_b32_e32 v97, v2
	v_mov_b32_e32 v106, v2
	v_mov_b32_e32 v107, v2
	v_mov_b32_e32 v108, v2
	v_mov_b32_e32 v109, v2
	v_mov_b32_e32 v110, v2
	v_mov_b32_e32 v111, v2
	v_mov_b32_e32 v112, v2
	v_mov_b32_e32 v113, v2
	v_mov_b32_e32 v122, v2
	v_mov_b32_e32 v123, v2
	v_mov_b32_e32 v124, v2
	v_mov_b32_e32 v125, v2
	v_mov_b32_e32 v126, v2
	v_mov_b32_e32 v127, v2
	v_mov_b32_e32 v128, v2
	v_mov_b32_e32 v129, v2
	.p2align	6

; template <class Epi, class Sched, bool ALIGN_EPI = false, bool SP2 = false>
; __device__ __forceinline__ void gemm_phase(PG8_LAS unsigned char* lds, const int Kdim, const Sched& S, const Epi& E) {
;     ...
;         for (int t = 0; t < nt; t += 2) {
;             const bool last = (t == nt - 2);
;             const char* a1 = cA + (size_t)(t + 1) * kstep;
;             const char* a2 = last ? nA : cA + (size_t)(t + 2) * kstep; const char* b2 = last ? nB : cB + (size_t)(t + 2) * kstep;
;             const char* a3 = a2 + kstep; const char* b3 = b2 + kstep;
.LBB0_2216:
	s_add_u32 s49, s20, 0x100
	s_addc_u32 s50, s21, 0
	v_lshl_add_u64 v[142:143], s[18:19], 0, v[134:135]
	v_lshl_add_u64 v[144:145], s[18:19], 0, v[136:137]
	s_mov_b32 s51, -2
	s_mov_b64 s[20:21], 0
	.p2align	6
